# attention early-stop check: row-min reduction by 4 DPP steps + 1 bpermute instead of 5 dependent ds_bpermute round trips
# baseline (speedup 1.0000x reference)
; __device__ __forceinline__ void attn_phase(LAS unsigned char* lds, const int wid, const bf16_t* P, const float* LF, bf16_t* CAT, const float* qgain, const float* kgain) {
;     ...
;                 if (kt * 64 <= q0 + 31 && !done_w && kt > 0) {
;                     float mmin = mrun;
; #pragma unroll
;                     for (int o = 1; o < 32; o <<= 1) mmin = fminf(mmin, __shfl_xor(mmin, o));
;                     done_w = (sbound + CB[kt * 64 - 1] < mmin) ? 1u : 0u;
;                 }
;                 if (lane == 0) flg[(it & 1) * 8 + wid] = done_w;
;                 if (more) {
.LBB0_277:
	v_max_f32_e32 v1, v166, v166
	v_mov_b32_e32 v3, s78
	ds_read_b32 v3, v3
	v_min_f32_dpp v1, v1, v1 quad_perm:[1,0,3,2] row_mask:0xf bank_mask:0xf
	s_nop 1
	v_min_f32_dpp v1, v1, v1 quad_perm:[2,3,0,1] row_mask:0xf bank_mask:0xf
	s_nop 1
	v_min_f32_dpp v1, v1, v1 row_half_mirror row_mask:0xf bank_mask:0xf
	s_nop 1
	v_min_f32_dpp v1, v1, v1 row_mirror row_mask:0xf bank_mask:0xf
	ds_bpermute_b32 v2, v145, v1
	s_waitcnt lgkmcnt(1)
	v_add_f32_e32 v3, v154, v3
	s_waitcnt lgkmcnt(0)
	v_max_f32_e32 v2, v2, v2
	v_min_f32_e32 v1, v1, v2
	v_cmp_lt_f32_e32 vcc, v3, v1
	s_nop 1
	v_cndmask_b32_e64 v165, 0, 1, vcc
	s_or_b64 exec, exec, s[18:19]
	s_and_saveexec_b64 s[18:19], s[4:5]
	s_cbranch_execz .LBB0_272
